# v18 with the four s_setprio of the attention loop removed
# baseline (speedup 1.0000x reference)
.LBB0_1410:
	s_lshl_b32 s0, s70, 14
	s_add_i32 s0, s0, 0
	s_add_i32 s0, s0, 0x12000
	v_add_u32_e32 v16, s0, v163
	ds_read_b64_tr_b16 v[226:227], v16 offset:0
	ds_read_b64_tr_b16 v[228:229], v16 offset:2048
	v_add_u32_e32 v17, s0, v212
	ds_read_b64_tr_b16 v[230:231], v17 offset:0
	ds_read_b64_tr_b16 v[232:233], v17 offset:2048
	ds_read_b64_tr_b16 v[234:235], v16 offset:1024
	ds_read_b64_tr_b16 v[236:237], v16 offset:3072
	v_exp_f32_e32 v34, v34
	v_exp_f32_e32 v35, v35
	v_add_f32_e32 v220, v220, v34
	v_add_f32_e32 v220, v220, v35
	v_exp_f32_e32 v36, v36
	v_exp_f32_e32 v37, v37
	v_add_f32_e32 v220, v220, v36
	v_add_f32_e32 v220, v220, v37
	v_exp_f32_e32 v38, v38
	v_exp_f32_e32 v39, v39
	v_add_f32_e32 v220, v220, v38
	v_add_f32_e32 v220, v220, v39
	v_exp_f32_e32 v40, v40
	v_exp_f32_e32 v41, v41
	v_add_f32_e32 v220, v220, v40
	v_add_f32_e32 v220, v220, v41
	v_cvt_pk_bf16_f32 v4, v34, v35
	v_cvt_pk_bf16_f32 v5, v36, v37
	v_cvt_pk_bf16_f32 v6, v38, v39
	v_cvt_pk_bf16_f32 v7, v40, v41
	s_nop 1
	ds_read_b64_tr_b16 v[238:239], v17 offset:1024
	ds_read_b64_tr_b16 v[240:241], v17 offset:3072
	s_waitcnt lgkmcnt(6)
	v_mfma_f32_32x32x16_bf16 v[98:113], v[226:229], v[4:7], v[98:113]
	ds_read_b64_tr_b16 v[226:227], v16 offset:4096
	ds_read_b64_tr_b16 v[228:229], v16 offset:6144
	v_exp_f32_e32 v42, v42
	v_exp_f32_e32 v43, v43
	v_add_f32_e32 v220, v220, v42
	v_add_f32_e32 v220, v220, v43
	s_waitcnt lgkmcnt(6)
	v_mfma_f32_32x32x16_bf16 v[82:97], v[230:233], v[4:7], v[82:97]
	ds_read_b64_tr_b16 v[230:231], v17 offset:4096
	ds_read_b64_tr_b16 v[232:233], v17 offset:6144
	v_exp_f32_e32 v44, v44
	v_exp_f32_e32 v45, v45
	v_add_f32_e32 v220, v220, v44
	v_add_f32_e32 v220, v220, v45
	s_waitcnt lgkmcnt(6)
	v_mfma_f32_32x32x16_bf16 v[66:81], v[234:237], v[4:7], v[66:81]
	ds_read_b64_tr_b16 v[234:235], v16 offset:5120
	ds_read_b64_tr_b16 v[236:237], v16 offset:7168
	v_exp_f32_e32 v46, v46
	v_exp_f32_e32 v47, v47
	v_add_f32_e32 v220, v220, v46
	v_add_f32_e32 v220, v220, v47
	s_waitcnt lgkmcnt(6)
	v_mfma_f32_32x32x16_bf16 v[50:65], v[238:241], v[4:7], v[50:65]
	ds_read_b64_tr_b16 v[4:5], v17 offset:5120
	ds_read_b64_tr_b16 v[6:7], v17 offset:7168
	v_exp_f32_e32 v48, v48
	v_exp_f32_e32 v49, v49
	v_add_f32_e32 v220, v220, v48
	v_add_f32_e32 v220, v220, v49
	v_cvt_pk_bf16_f32 v8, v42, v43
	v_cvt_pk_bf16_f32 v9, v44, v45
	v_cvt_pk_bf16_f32 v10, v46, v47
	v_cvt_pk_bf16_f32 v11, v48, v49
	s_nop 1
	s_waitcnt lgkmcnt(6)
	v_mfma_f32_32x32x16_bf16 v[98:113], v[226:229], v[8:11], v[98:113]
	ds_read_b64_tr_b16 v[226:227], v16 offset:8192
	ds_read_b64_tr_b16 v[228:229], v16 offset:10240
	v_exp_f32_e32 v18, v18
	v_exp_f32_e32 v19, v19
	v_add_f32_e32 v220, v220, v18
	v_add_f32_e32 v220, v220, v19
	s_waitcnt lgkmcnt(6)
	v_mfma_f32_32x32x16_bf16 v[82:97], v[230:233], v[8:11], v[82:97]
	ds_read_b64_tr_b16 v[230:231], v17 offset:8192
	ds_read_b64_tr_b16 v[232:233], v17 offset:10240
	v_exp_f32_e32 v20, v20
	v_exp_f32_e32 v21, v21
	v_add_f32_e32 v220, v220, v20
	v_add_f32_e32 v220, v220, v21
	s_waitcnt lgkmcnt(6)
	v_mfma_f32_32x32x16_bf16 v[66:81], v[234:237], v[8:11], v[66:81]
	ds_read_b64_tr_b16 v[234:235], v16 offset:9216
	ds_read_b64_tr_b16 v[236:237], v16 offset:11264
	v_exp_f32_e32 v22, v22
	v_exp_f32_e32 v23, v23
	v_add_f32_e32 v220, v220, v22
	v_add_f32_e32 v220, v220, v23
	s_waitcnt lgkmcnt(6)
	v_mfma_f32_32x32x16_bf16 v[50:65], v[4:7], v[8:11], v[50:65]
	ds_read_b64_tr_b16 v[4:5], v17 offset:9216
	ds_read_b64_tr_b16 v[6:7], v17 offset:11264
	v_exp_f32_e32 v24, v24
	v_exp_f32_e32 v25, v25
	v_add_f32_e32 v220, v220, v24
	v_add_f32_e32 v220, v220, v25
	v_cvt_pk_bf16_f32 v12, v18, v19
	v_cvt_pk_bf16_f32 v13, v20, v21
	v_cvt_pk_bf16_f32 v14, v22, v23
	v_cvt_pk_bf16_f32 v15, v24, v25
	s_nop 1
	s_waitcnt lgkmcnt(6)
	v_mfma_f32_32x32x16_bf16 v[98:113], v[226:229], v[12:15], v[98:113]
	ds_read_b64_tr_b16 v[8:9], v16 offset:12288
	ds_read_b64_tr_b16 v[10:11], v16 offset:14336
	v_exp_f32_e32 v26, v26
	v_exp_f32_e32 v27, v27
	v_add_f32_e32 v220, v220, v26
	v_add_f32_e32 v220, v220, v27
	s_waitcnt lgkmcnt(6)
	v_mfma_f32_32x32x16_bf16 v[82:97], v[230:233], v[12:15], v[82:97]
	ds_read_b64_tr_b16 v[226:227], v17 offset:12288
	ds_read_b64_tr_b16 v[228:229], v17 offset:14336
	v_exp_f32_e32 v28, v28
	v_exp_f32_e32 v29, v29
	v_add_f32_e32 v220, v220, v28
	v_add_f32_e32 v220, v220, v29
	s_waitcnt lgkmcnt(6)
	v_mfma_f32_32x32x16_bf16 v[66:81], v[234:237], v[12:15], v[66:81]
	ds_read_b64_tr_b16 v[230:231], v16 offset:13312
	ds_read_b64_tr_b16 v[232:233], v16 offset:15360
	v_exp_f32_e32 v30, v30
	v_exp_f32_e32 v31, v31
	v_add_f32_e32 v220, v220, v30
	v_add_f32_e32 v220, v220, v31
	s_waitcnt lgkmcnt(6)
	v_mfma_f32_32x32x16_bf16 v[50:65], v[4:7], v[12:15], v[50:65]
	ds_read_b64_tr_b16 v[4:5], v17 offset:13312
	ds_read_b64_tr_b16 v[6:7], v17 offset:15360
	v_exp_f32_e32 v32, v32
	v_exp_f32_e32 v33, v33
	v_add_f32_e32 v220, v220, v32
	v_add_f32_e32 v220, v220, v33
	v_cvt_pk_bf16_f32 v222, v26, v27
	v_cvt_pk_bf16_f32 v223, v28, v29
	v_cvt_pk_bf16_f32 v224, v30, v31
	v_cvt_pk_bf16_f32 v225, v32, v33
	s_nop 1
	s_waitcnt lgkmcnt(6)
	v_mfma_f32_32x32x16_bf16 v[98:113], v[8:11], v[222:225], v[98:113]
	s_waitcnt lgkmcnt(4)
	v_mfma_f32_32x32x16_bf16 v[82:97], v[226:229], v[222:225], v[82:97]
	s_waitcnt lgkmcnt(2)
	v_mfma_f32_32x32x16_bf16 v[66:81], v[230:233], v[222:225], v[66:81]
	s_waitcnt lgkmcnt(0)
	v_mfma_f32_32x32x16_bf16 v[50:65], v[4:7], v[222:225], v[50:65]

.LBB0_1417:
	s_barrier
	s_cmp_le_u32 s16, s18
	s_cselect_b64 s[12:13], -1, 0
	s_cmp_gt_u32 s16, s18
	s_mul_i32 s17, s3, 0x6000
	s_cbranch_scc1 .LBB0_1419
	s_add_i32 s0, s17, 0
	v_add_u32_e32 v16, s0, v213
	v_add_u32_e32 v17, v16, v214
	ds_read_b128 v[4:7], v17 offset:0
	ds_read_b128 v[8:11], v17 offset:12288
	v_add_u32_e32 v221, v16, v215
	ds_read_b128 v[12:15], v221 offset:0
	ds_read_b128 v[222:225], v221 offset:12288
	v_xor_b32_e32 v18, 0x80000000, v3
	v_mov_b32_e32 v19, v18
	v_mov_b32_e32 v20, v18
	v_mov_b32_e32 v21, v18
	v_mov_b32_e32 v22, v18
	v_mov_b32_e32 v23, v18
	v_mov_b32_e32 v24, v18
	v_mov_b32_e32 v25, v18
	v_mov_b32_e32 v26, v18
	v_mov_b32_e32 v27, v18
	v_mov_b32_e32 v28, v18
	v_mov_b32_e32 v29, v18
	v_mov_b32_e32 v30, v18
	v_mov_b32_e32 v31, v18
	v_mov_b32_e32 v32, v18
	v_mov_b32_e32 v33, v18
	v_add_u32_e32 v234, v16, v216
	ds_read_b128 v[226:229], v234 offset:0
	ds_read_b128 v[230:233], v234 offset:12288
	s_waitcnt lgkmcnt(4)
	v_mfma_f32_32x32x16_bf16 v[34:49], v[4:7], v[114:117], v[18:33]
	v_mfma_f32_32x32x16_bf16 v[18:33], v[8:11], v[114:117], v[18:33]
	v_add_u32_e32 v16, v16, v217
	ds_read_b128 v[4:7], v16 offset:0
	ds_read_b128 v[8:11], v16 offset:12288
	s_waitcnt lgkmcnt(4)
	v_mfma_f32_32x32x16_bf16 v[34:49], v[12:15], v[118:121], v[34:49]
	v_mfma_f32_32x32x16_bf16 v[18:33], v[222:225], v[118:121], v[18:33]
	ds_read_b128 v[12:15], v17 offset:4096
	ds_read_b128 v[222:225], v17 offset:16384
	s_waitcnt lgkmcnt(4)
	v_mfma_f32_32x32x16_bf16 v[34:49], v[226:229], v[122:125], v[34:49]
	v_mfma_f32_32x32x16_bf16 v[18:33], v[230:233], v[122:125], v[18:33]
	ds_read_b128 v[226:229], v221 offset:4096
	ds_read_b128 v[230:233], v221 offset:16384
	s_waitcnt lgkmcnt(4)
	v_mfma_f32_32x32x16_bf16 v[34:49], v[4:7], v[126:129], v[34:49]
	v_mfma_f32_32x32x16_bf16 v[18:33], v[8:11], v[126:129], v[18:33]
	ds_read_b128 v[4:7], v234 offset:4096
	ds_read_b128 v[8:11], v234 offset:16384
	s_waitcnt lgkmcnt(4)
	v_mfma_f32_32x32x16_bf16 v[34:49], v[12:15], v[130:133], v[34:49]
	v_mfma_f32_32x32x16_bf16 v[18:33], v[222:225], v[130:133], v[18:33]
	ds_read_b128 v[12:15], v16 offset:4096
	ds_read_b128 v[222:225], v16 offset:16384
	s_waitcnt lgkmcnt(4)
	v_mfma_f32_32x32x16_bf16 v[34:49], v[226:229], v[134:137], v[34:49]
	v_mfma_f32_32x32x16_bf16 v[18:33], v[230:233], v[134:137], v[18:33]
	ds_read_b128 v[226:229], v17 offset:8192
	ds_read_b128 v[230:233], v17 offset:20480
	s_waitcnt lgkmcnt(4)
	v_mfma_f32_32x32x16_bf16 v[34:49], v[4:7], v[138:141], v[34:49]
	v_mfma_f32_32x32x16_bf16 v[18:33], v[8:11], v[138:141], v[18:33]
	ds_read_b128 v[4:7], v221 offset:8192
	ds_read_b128 v[8:11], v221 offset:20480
	s_waitcnt lgkmcnt(4)
	v_mfma_f32_32x32x16_bf16 v[34:49], v[12:15], v[142:145], v[34:49]
	v_mfma_f32_32x32x16_bf16 v[18:33], v[222:225], v[142:145], v[18:33]
	ds_read_b128 v[12:15], v234 offset:8192
	ds_read_b128 v[222:225], v234 offset:20480
	s_waitcnt lgkmcnt(4)
	v_mfma_f32_32x32x16_bf16 v[34:49], v[226:229], v[146:149], v[34:49]
	v_mfma_f32_32x32x16_bf16 v[18:33], v[230:233], v[146:149], v[18:33]
	ds_read_b128 v[226:229], v16 offset:8192
	ds_read_b128 v[230:233], v16 offset:20480
	s_waitcnt lgkmcnt(4)
	v_mfma_f32_32x32x16_bf16 v[34:49], v[4:7], v[150:153], v[34:49]
	v_mfma_f32_32x32x16_bf16 v[18:33], v[8:11], v[150:153], v[18:33]
	s_waitcnt lgkmcnt(2)
	v_mfma_f32_32x32x16_bf16 v[34:49], v[12:15], v[154:157], v[34:49]
	v_mfma_f32_32x32x16_bf16 v[18:33], v[222:225], v[154:157], v[18:33]
	s_waitcnt lgkmcnt(0)
	v_mfma_f32_32x32x16_bf16 v[34:49], v[226:229], v[158:161], v[34:49]
	v_mfma_f32_32x32x16_bf16 v[18:33], v[230:233], v[158:161], v[18:33]
